# UP K-loops: first iteration peeled with C=0 on each accumulator's first MFMA; the 128 accumulator-zeroing v_mov per tile removed
# speedup vs baseline: 1.0078x; 1.0034x over previous
.LBB0_556:
	s_ashr_i32 s41, s40, 31
	s_lshl_b64 s[42:43], s[40:41], 19
	s_add_u32 s42, s68, s42
	s_addc_u32 s43, s69, s43
	s_and_b64 s[44:45], s[4:5], exec
	s_cselect_b32 s41, s43, s9
	s_cselect_b32 s47, s42, s8
	s_ashr_i32 s39, s38, 31
	s_lshl_b64 s[44:45], s[38:39], 19
	s_add_u32 s44, s54, s44
	s_addc_u32 s45, s55, s45
	s_and_b64 s[50:51], s[4:5], exec
	s_cselect_b32 s39, s45, s49
	s_cselect_b32 vcc_lo, s44, s48
	s_add_u32 s8, s8, 0x40080
	s_addc_u32 s9, s9, 0
	s_add_u32 vcc_hi, s48, 0x100
	s_addc_u32 s3, s49, 0
	s_mov_b32 s7, -2
	s_waitcnt lgkmcnt(0)
	ds_read_b128 v[30:33], v219
	ds_read_b128 v[54:57], v219 offset:1024
	ds_read_b128 v[118:121], v219 offset:2048
	ds_read_b128 v[122:125], v219 offset:3072
	ds_read_b128 v[146:149], v220
	ds_read_b128 v[150:153], v220 offset:1024
	ds_read_b128 v[154:157], v220 offset:2048
	ds_read_b128 v[158:161], v220 offset:3072
	s_add_u32 s48, s8, 0xfffc0080
	s_addc_u32 s49, s9, -1
	s_cmp_eq_u32 s7, 12
	s_cselect_b32 s51, s41, s49
	s_cselect_b32 s50, s47, s48
	s_cselect_b32 s49, s39, s3
	s_cselect_b32 s48, vcc_lo, vcc_hi
	s_add_i32 m0, s70, 0xc000
	ds_read_b128 v[162:165], v221
	ds_read_b128 v[166:169], v221 offset:1024
	ds_read_b128 v[194:197], v221 offset:2048
	ds_read_b128 v[198:201], v221 offset:3072
	ds_read_b128 v[202:205], v221 offset:4096
	ds_read_b128 v[206:209], v221 offset:5120
	ds_read_b128 v[224:227], v221 offset:6144
	ds_read_b128 v[228:231], v221 offset:7168
	global_load_lds_dwordx4 v186, s[8:9]
	s_add_i32 m0, s70, 0xe000
	s_nop 0
	global_load_lds_dwordx4 v188, s[8:9]
	s_waitcnt vmcnt(8)
	s_waitcnt lgkmcnt(0)
	s_barrier
	s_setprio 1
	v_mfma_f32_16x16x32_bf16 v[62:65], v[30:33], v[162:165], 0
	v_mfma_f32_16x16x32_bf16 v[42:45], v[118:121], v[162:165], 0
	v_mfma_f32_16x16x32_bf16 v[50:53], v[30:33], v[194:197], 0
	v_mfma_f32_16x16x32_bf16 v[38:41], v[118:121], v[194:197], 0
	v_mfma_f32_16x16x32_bf16 v[46:49], v[30:33], v[202:205], 0
	v_mfma_f32_16x16x32_bf16 v[34:37], v[118:121], v[202:205], 0
	v_mfma_f32_16x16x32_bf16 v[142:145], v[30:33], v[224:227], 0
	v_mfma_f32_16x16x32_bf16 v[82:85], v[118:121], v[224:227], 0
	v_mfma_f32_16x16x32_bf16 v[62:65], v[54:57], v[166:169], v[62:65]
	v_mfma_f32_16x16x32_bf16 v[42:45], v[122:125], v[166:169], v[42:45]
	v_mfma_f32_16x16x32_bf16 v[50:53], v[54:57], v[198:201], v[50:53]
	v_mfma_f32_16x16x32_bf16 v[38:41], v[122:125], v[198:201], v[38:41]
	v_mfma_f32_16x16x32_bf16 v[46:49], v[54:57], v[206:209], v[46:49]
	v_mfma_f32_16x16x32_bf16 v[34:37], v[122:125], v[206:209], v[34:37]
	v_mfma_f32_16x16x32_bf16 v[142:145], v[54:57], v[228:231], v[142:145]
	v_mfma_f32_16x16x32_bf16 v[82:85], v[122:125], v[228:231], v[82:85]
	v_mfma_f32_16x16x32_bf16 v[134:137], v[146:149], v[162:165], 0
	v_mfma_f32_16x16x32_bf16 v[74:77], v[154:157], v[162:165], 0
	v_mfma_f32_16x16x32_bf16 v[130:133], v[146:149], v[194:197], 0
	v_mfma_f32_16x16x32_bf16 v[70:73], v[154:157], v[194:197], 0
	v_mfma_f32_16x16x32_bf16 v[78:81], v[146:149], v[202:205], 0
	v_mfma_f32_16x16x32_bf16 v[66:69], v[154:157], v[202:205], 0
	v_mfma_f32_16x16x32_bf16 v[138:141], v[146:149], v[224:227], 0
	v_mfma_f32_16x16x32_bf16 v[98:101], v[154:157], v[224:227], 0
	v_mfma_f32_16x16x32_bf16 v[134:137], v[150:153], v[166:169], v[134:137]
	v_mfma_f32_16x16x32_bf16 v[74:77], v[158:161], v[166:169], v[74:77]
	v_mfma_f32_16x16x32_bf16 v[130:133], v[150:153], v[198:201], v[130:133]
	v_mfma_f32_16x16x32_bf16 v[70:73], v[158:161], v[198:201], v[70:73]
	v_mfma_f32_16x16x32_bf16 v[78:81], v[150:153], v[206:209], v[78:81]
	v_mfma_f32_16x16x32_bf16 v[66:69], v[158:161], v[206:209], v[66:69]
	v_mfma_f32_16x16x32_bf16 v[138:141], v[150:153], v[228:231], v[138:141]
	v_mfma_f32_16x16x32_bf16 v[98:101], v[158:161], v[228:231], v[98:101]
	s_setprio 0
	s_barrier
	s_add_u32 s98, s48, 0x80
	s_addc_u32 s99, s49, 0
	s_add_u32 s100, s50, 0x80
	s_addc_u32 s101, s51, 0
	s_add_i32 s84, s93, s64
	s_mov_b32 m0, s84
	ds_read_b128 v[162:165], v221 offset:16384
	ds_read_b128 v[166:169], v221 offset:17408
	ds_read_b128 v[194:197], v221 offset:18432
	ds_read_b128 v[198:201], v221 offset:19456
	ds_read_b128 v[202:205], v221 offset:20480
	ds_read_b128 v[206:209], v221 offset:21504
	ds_read_b128 v[224:227], v221 offset:22528
	ds_read_b128 v[228:231], v221 offset:23552
	global_load_lds_dwordx4 v176, s[48:49]
	s_add_i32 m0, s84, 0x2000
	s_add_u32 s84, s48, 0x40000
	s_addc_u32 s85, s49, 0
	s_add_i32 s86, s90, s64
	global_load_lds_dwordx4 v180, s[48:49]
	s_mov_b32 m0, s86
	s_nop 0
	global_load_lds_dwordx4 v176, s[84:85]
	s_add_i32 m0, s86, 0x2000
	s_nop 0
	global_load_lds_dwordx4 v180, s[84:85]
	s_mov_b32 m0, s70
	s_nop 0
	global_load_lds_dwordx4 v174, s[50:51]
	s_mov_b32 m0, s71
	s_nop 0
	global_load_lds_dwordx4 v178, s[50:51]
	s_waitcnt vmcnt(8)
	s_waitcnt lgkmcnt(0)
	s_barrier
	s_setprio 1
	v_mfma_f32_16x16x32_bf16 v[94:97], v[30:33], v[162:165], 0
	v_mfma_f32_16x16x32_bf16 v[10:13], v[118:121], v[162:165], 0
	v_mfma_f32_16x16x32_bf16 v[90:93], v[30:33], v[194:197], 0
	v_mfma_f32_16x16x32_bf16 v[6:9], v[118:121], v[194:197], 0
	v_mfma_f32_16x16x32_bf16 v[86:89], v[30:33], v[202:205], 0
	v_mfma_f32_16x16x32_bf16 v[2:5], v[118:121], v[202:205], 0
	v_mfma_f32_16x16x32_bf16 v[26:29], v[118:121], v[224:227], 0
	v_mfma_f32_16x16x32_bf16 v[94:97], v[54:57], v[166:169], v[94:97]
	v_mfma_f32_16x16x32_bf16 v[10:13], v[122:125], v[166:169], v[10:13]
	v_mfma_f32_16x16x32_bf16 v[90:93], v[54:57], v[198:201], v[90:93]
	v_mfma_f32_16x16x32_bf16 v[6:9], v[122:125], v[198:201], v[6:9]
	v_mfma_f32_16x16x32_bf16 v[86:89], v[54:57], v[206:209], v[86:89]
	v_mfma_f32_16x16x32_bf16 v[2:5], v[122:125], v[206:209], v[2:5]
	v_mfma_f32_16x16x32_bf16 v[30:33], v[30:33], v[224:227], 0
	v_mfma_f32_16x16x32_bf16 v[26:29], v[122:125], v[228:231], v[26:29]
	v_mfma_f32_16x16x32_bf16 v[30:33], v[54:57], v[228:231], v[30:33]
	v_mfma_f32_16x16x32_bf16 v[22:25], v[154:157], v[162:165], 0
	v_mfma_f32_16x16x32_bf16 v[106:109], v[146:149], v[194:197], 0
	v_mfma_f32_16x16x32_bf16 v[18:21], v[154:157], v[194:197], 0
	v_mfma_f32_16x16x32_bf16 v[102:105], v[146:149], v[202:205], 0
	v_mfma_f32_16x16x32_bf16 v[14:17], v[154:157], v[202:205], 0
	v_mfma_f32_16x16x32_bf16 v[58:61], v[154:157], v[224:227], 0
	v_mfma_f32_16x16x32_bf16 v[54:57], v[146:149], v[162:165], 0
	v_mfma_f32_16x16x32_bf16 v[22:25], v[158:161], v[166:169], v[22:25]
	v_mfma_f32_16x16x32_bf16 v[106:109], v[150:153], v[198:201], v[106:109]
	v_mfma_f32_16x16x32_bf16 v[18:21], v[158:161], v[198:201], v[18:21]
	v_mfma_f32_16x16x32_bf16 v[102:105], v[150:153], v[206:209], v[102:105]
	v_mfma_f32_16x16x32_bf16 v[14:17], v[158:161], v[206:209], v[14:17]
	v_mfma_f32_16x16x32_bf16 v[110:113], v[146:149], v[224:227], 0
	v_mfma_f32_16x16x32_bf16 v[58:61], v[158:161], v[228:231], v[58:61]
	v_mfma_f32_16x16x32_bf16 v[54:57], v[150:153], v[166:169], v[54:57]
	v_mfma_f32_16x16x32_bf16 v[118:121], v[150:153], v[228:231], v[110:113]
	s_setprio 0
	s_barrier
	s_add_i32 s84, 0, 0x18000
	v_add_u32_e32 v1, s84, v210
	s_add_i32 s85, 0, 0x1c000
	ds_read_b128 v[110:113], v1
	ds_read_b128 v[114:117], v1 offset:1024
	ds_read_b128 v[122:125], v1 offset:2048
	ds_read_b128 v[126:129], v1 offset:3072
	v_add_u32_e32 v1, s85, v210
	ds_read_b128 v[146:149], v1
	ds_read_b128 v[150:153], v1 offset:1024
	ds_read_b128 v[154:157], v1 offset:2048
	ds_read_b128 v[158:161], v1 offset:3072
	s_add_u32 s50, s50, 0x40000
	s_addc_u32 s51, s51, 0
	s_mov_b32 m0, s74
	ds_read_b128 v[162:165], v221 offset:32768
	ds_read_b128 v[166:169], v221 offset:33792
	ds_read_b128 v[194:197], v221 offset:34816
	ds_read_b128 v[198:201], v221 offset:35840
	ds_read_b128 v[202:205], v221 offset:36864
	ds_read_b128 v[206:209], v221 offset:37888
	ds_read_b128 v[224:227], v221 offset:38912
	ds_read_b128 v[228:231], v221 offset:39936
	global_load_lds_dwordx4 v174, s[50:51]
	s_mov_b32 m0, s75
	s_nop 0
	global_load_lds_dwordx4 v178, s[50:51]
	s_waitcnt vmcnt(8)
	s_waitcnt lgkmcnt(0)
	s_barrier
	s_setprio 1
	v_mfma_f32_16x16x32_bf16 v[62:65], v[110:113], v[162:165], v[62:65]
	v_mfma_f32_16x16x32_bf16 v[42:45], v[122:125], v[162:165], v[42:45]
	v_mfma_f32_16x16x32_bf16 v[50:53], v[110:113], v[194:197], v[50:53]
	v_mfma_f32_16x16x32_bf16 v[38:41], v[122:125], v[194:197], v[38:41]
	v_mfma_f32_16x16x32_bf16 v[46:49], v[110:113], v[202:205], v[46:49]
	v_mfma_f32_16x16x32_bf16 v[34:37], v[122:125], v[202:205], v[34:37]
	v_mfma_f32_16x16x32_bf16 v[142:145], v[110:113], v[224:227], v[142:145]
	v_mfma_f32_16x16x32_bf16 v[82:85], v[122:125], v[224:227], v[82:85]
	v_mfma_f32_16x16x32_bf16 v[62:65], v[114:117], v[166:169], v[62:65]
	v_mfma_f32_16x16x32_bf16 v[42:45], v[126:129], v[166:169], v[42:45]
	v_mfma_f32_16x16x32_bf16 v[50:53], v[114:117], v[198:201], v[50:53]
	v_mfma_f32_16x16x32_bf16 v[38:41], v[126:129], v[198:201], v[38:41]
	v_mfma_f32_16x16x32_bf16 v[46:49], v[114:117], v[206:209], v[46:49]
	v_mfma_f32_16x16x32_bf16 v[34:37], v[126:129], v[206:209], v[34:37]
	v_mfma_f32_16x16x32_bf16 v[142:145], v[114:117], v[228:231], v[142:145]
	v_mfma_f32_16x16x32_bf16 v[82:85], v[126:129], v[228:231], v[82:85]
	v_mfma_f32_16x16x32_bf16 v[134:137], v[146:149], v[162:165], v[134:137]
	v_mfma_f32_16x16x32_bf16 v[74:77], v[154:157], v[162:165], v[74:77]
	v_mfma_f32_16x16x32_bf16 v[130:133], v[146:149], v[194:197], v[130:133]
	v_mfma_f32_16x16x32_bf16 v[70:73], v[154:157], v[194:197], v[70:73]
	v_mfma_f32_16x16x32_bf16 v[78:81], v[146:149], v[202:205], v[78:81]
	v_mfma_f32_16x16x32_bf16 v[66:69], v[154:157], v[202:205], v[66:69]
	v_mfma_f32_16x16x32_bf16 v[138:141], v[146:149], v[224:227], v[138:141]
	v_mfma_f32_16x16x32_bf16 v[98:101], v[154:157], v[224:227], v[98:101]
	v_mfma_f32_16x16x32_bf16 v[134:137], v[150:153], v[166:169], v[134:137]
	v_mfma_f32_16x16x32_bf16 v[74:77], v[158:161], v[166:169], v[74:77]
	v_mfma_f32_16x16x32_bf16 v[130:133], v[150:153], v[198:201], v[130:133]
	v_mfma_f32_16x16x32_bf16 v[70:73], v[158:161], v[198:201], v[70:73]
	v_mfma_f32_16x16x32_bf16 v[78:81], v[150:153], v[206:209], v[78:81]
	v_mfma_f32_16x16x32_bf16 v[66:69], v[158:161], v[206:209], v[66:69]
	v_mfma_f32_16x16x32_bf16 v[138:141], v[150:153], v[228:231], v[138:141]
	v_mfma_f32_16x16x32_bf16 v[98:101], v[158:161], v[228:231], v[98:101]
	s_setprio 0
	s_barrier
	s_add_i32 s50, s84, s64
	s_mov_b32 m0, s50
	ds_read_b128 v[162:165], v221 offset:49152
	ds_read_b128 v[166:169], v221 offset:50176
	ds_read_b128 v[194:197], v221 offset:51200
	ds_read_b128 v[198:201], v221 offset:52224
	ds_read_b128 v[202:205], v221 offset:53248
	ds_read_b128 v[206:209], v221 offset:54272
	ds_read_b128 v[224:227], v221 offset:55296
	ds_read_b128 v[228:231], v221 offset:56320
	global_load_lds_dwordx4 v176, s[98:99]
	s_add_i32 m0, s50, 0x2000
	s_add_u32 s48, s48, 0x40080
	s_addc_u32 s49, s49, 0
	s_add_i32 s50, s85, s64
	global_load_lds_dwordx4 v180, s[98:99]
	s_mov_b32 m0, s50
	s_nop 0
	global_load_lds_dwordx4 v176, s[48:49]
	s_add_i32 m0, s50, 0x2000
	s_nop 0
	global_load_lds_dwordx4 v180, s[48:49]
	s_mov_b32 m0, s77
	s_nop 0
	global_load_lds_dwordx4 v174, s[100:101]
	s_mov_b32 m0, s78
	s_nop 0
	global_load_lds_dwordx4 v178, s[100:101]
	s_waitcnt vmcnt(8)
	s_waitcnt lgkmcnt(0)
	s_barrier
	s_setprio 1
	v_mfma_f32_16x16x32_bf16 v[94:97], v[110:113], v[162:165], v[94:97]
	v_mfma_f32_16x16x32_bf16 v[10:13], v[122:125], v[162:165], v[10:13]
	v_mfma_f32_16x16x32_bf16 v[90:93], v[110:113], v[194:197], v[90:93]
	v_mfma_f32_16x16x32_bf16 v[6:9], v[122:125], v[194:197], v[6:9]
	v_mfma_f32_16x16x32_bf16 v[86:89], v[110:113], v[202:205], v[86:89]
	v_mfma_f32_16x16x32_bf16 v[2:5], v[122:125], v[202:205], v[2:5]
	v_mfma_f32_16x16x32_bf16 v[30:33], v[110:113], v[224:227], v[30:33]
	v_mfma_f32_16x16x32_bf16 v[26:29], v[122:125], v[224:227], v[26:29]
	v_mfma_f32_16x16x32_bf16 v[94:97], v[114:117], v[166:169], v[94:97]
	v_mfma_f32_16x16x32_bf16 v[10:13], v[126:129], v[166:169], v[10:13]
	v_mfma_f32_16x16x32_bf16 v[90:93], v[114:117], v[198:201], v[90:93]
	v_mfma_f32_16x16x32_bf16 v[6:9], v[126:129], v[198:201], v[6:9]
	v_mfma_f32_16x16x32_bf16 v[86:89], v[114:117], v[206:209], v[86:89]
	v_mfma_f32_16x16x32_bf16 v[2:5], v[126:129], v[206:209], v[2:5]
	v_mfma_f32_16x16x32_bf16 v[114:117], v[114:117], v[228:231], v[30:33]
	v_mfma_f32_16x16x32_bf16 v[26:29], v[126:129], v[228:231], v[26:29]
	v_mfma_f32_16x16x32_bf16 v[30:33], v[146:149], v[162:165], v[54:57]
	v_mfma_f32_16x16x32_bf16 v[110:113], v[150:153], v[166:169], v[30:33]
	v_mfma_f32_16x16x32_bf16 v[30:33], v[146:149], v[194:197], v[106:109]
	v_mfma_f32_16x16x32_bf16 v[106:109], v[150:153], v[198:201], v[30:33]
	v_mfma_f32_16x16x32_bf16 v[30:33], v[146:149], v[202:205], v[102:105]
	v_mfma_f32_16x16x32_bf16 v[102:105], v[150:153], v[206:209], v[30:33]
	v_mfma_f32_16x16x32_bf16 v[30:33], v[146:149], v[224:227], v[118:121]
	v_mfma_f32_16x16x32_bf16 v[22:25], v[154:157], v[162:165], v[22:25]
	v_mfma_f32_16x16x32_bf16 v[18:21], v[154:157], v[194:197], v[18:21]
	v_mfma_f32_16x16x32_bf16 v[14:17], v[154:157], v[202:205], v[14:17]
	v_mfma_f32_16x16x32_bf16 v[126:129], v[150:153], v[228:231], v[30:33]
	v_mfma_f32_16x16x32_bf16 v[30:33], v[154:157], v[224:227], v[58:61]
	v_mfma_f32_16x16x32_bf16 v[22:25], v[158:161], v[166:169], v[22:25]
	v_mfma_f32_16x16x32_bf16 v[18:21], v[158:161], v[198:201], v[18:21]
	v_mfma_f32_16x16x32_bf16 v[14:17], v[158:161], v[206:209], v[14:17]
	v_mfma_f32_16x16x32_bf16 v[58:61], v[158:161], v[228:231], v[30:33]
	s_setprio 0
	s_barrier
	s_add_i32 s7, s7, 2
	s_add_u32 s8, s8, 0x100
	s_addc_u32 s9, s9, 0
	s_add_u32 vcc_hi, vcc_hi, 0x100
	s_addc_u32 s3, s3, 0
	s_cmp_gt_u32 s7, 13

.LBB0_1316:
	s_ashr_i32 s45, s44, 31
	s_lshl_b64 s[46:47], s[44:45], 19
	s_add_u32 s46, s68, s46
	s_addc_u32 s47, s69, s47
	s_and_b64 s[48:49], s[4:5], exec
	s_cselect_b32 s45, s47, s9
	s_cselect_b32 s51, s46, s8
	s_ashr_i32 s43, s42, 31
	s_lshl_b64 s[48:49], s[42:43], 19
	s_add_u32 s48, s7, s48
	s_addc_u32 s49, s56, s49
	s_and_b64 s[54:55], s[4:5], exec
	s_cselect_b32 s43, s49, s53
	s_cselect_b32 s90, s48, s52
	s_add_u32 s8, s8, 0x40080
	s_addc_u32 s9, s9, 0
	s_add_u32 s91, s52, 0x100
	s_addc_u32 s92, s53, 0
	s_mov_b32 s93, -2
	ds_read_b128 v[30:33], v219
	ds_read_b128 v[54:57], v219 offset:1024
	ds_read_b128 v[118:121], v219 offset:2048
	ds_read_b128 v[122:125], v219 offset:3072
	ds_read_b128 v[146:149], v220
	ds_read_b128 v[150:153], v220 offset:1024
	ds_read_b128 v[154:157], v220 offset:2048
	ds_read_b128 v[158:161], v220 offset:3072
	s_add_u32 s52, s8, 0xfffc0080
	s_addc_u32 s53, s9, -1
	s_cmp_eq_u32 s93, 12
	s_cselect_b32 s55, s45, s53
	s_cselect_b32 s54, s51, s52
	s_cselect_b32 s53, s43, s92
	s_cselect_b32 s52, s90, s91
	s_add_i32 m0, s59, 0xc000
	ds_read_b128 v[162:165], v221
	ds_read_b128 v[166:169], v221 offset:1024
	ds_read_b128 v[196:199], v221 offset:2048
	ds_read_b128 v[200:203], v221 offset:3072
	ds_read_b128 v[204:207], v221 offset:4096
	ds_read_b128 v[208:211], v221 offset:5120
	ds_read_b128 v[224:227], v221 offset:6144
	ds_read_b128 v[228:231], v221 offset:7168
	global_load_lds_dwordx4 v188, s[8:9]
	s_add_i32 m0, s59, 0xe000
	s_nop 0
	global_load_lds_dwordx4 v190, s[8:9]
	s_waitcnt vmcnt(8)
	s_waitcnt lgkmcnt(0)
	s_barrier
	s_setprio 1
	v_mfma_f32_16x16x32_bf16 v[62:65], v[30:33], v[162:165], 0
	v_mfma_f32_16x16x32_bf16 v[42:45], v[118:121], v[162:165], 0
	v_mfma_f32_16x16x32_bf16 v[50:53], v[30:33], v[196:199], 0
	v_mfma_f32_16x16x32_bf16 v[38:41], v[118:121], v[196:199], 0
	v_mfma_f32_16x16x32_bf16 v[46:49], v[30:33], v[204:207], 0
	v_mfma_f32_16x16x32_bf16 v[34:37], v[118:121], v[204:207], 0
	v_mfma_f32_16x16x32_bf16 v[142:145], v[30:33], v[224:227], 0
	v_mfma_f32_16x16x32_bf16 v[82:85], v[118:121], v[224:227], 0
	v_mfma_f32_16x16x32_bf16 v[62:65], v[54:57], v[166:169], v[62:65]
	v_mfma_f32_16x16x32_bf16 v[42:45], v[122:125], v[166:169], v[42:45]
	v_mfma_f32_16x16x32_bf16 v[50:53], v[54:57], v[200:203], v[50:53]
	v_mfma_f32_16x16x32_bf16 v[38:41], v[122:125], v[200:203], v[38:41]
	v_mfma_f32_16x16x32_bf16 v[46:49], v[54:57], v[208:211], v[46:49]
	v_mfma_f32_16x16x32_bf16 v[34:37], v[122:125], v[208:211], v[34:37]
	v_mfma_f32_16x16x32_bf16 v[142:145], v[54:57], v[228:231], v[142:145]
	v_mfma_f32_16x16x32_bf16 v[82:85], v[122:125], v[228:231], v[82:85]
	v_mfma_f32_16x16x32_bf16 v[134:137], v[146:149], v[162:165], 0
	v_mfma_f32_16x16x32_bf16 v[74:77], v[154:157], v[162:165], 0
	v_mfma_f32_16x16x32_bf16 v[130:133], v[146:149], v[196:199], 0
	v_mfma_f32_16x16x32_bf16 v[70:73], v[154:157], v[196:199], 0
	v_mfma_f32_16x16x32_bf16 v[78:81], v[146:149], v[204:207], 0
	v_mfma_f32_16x16x32_bf16 v[66:69], v[154:157], v[204:207], 0
	v_mfma_f32_16x16x32_bf16 v[138:141], v[146:149], v[224:227], 0
	v_mfma_f32_16x16x32_bf16 v[98:101], v[154:157], v[224:227], 0
	v_mfma_f32_16x16x32_bf16 v[134:137], v[150:153], v[166:169], v[134:137]
	v_mfma_f32_16x16x32_bf16 v[74:77], v[158:161], v[166:169], v[74:77]
	v_mfma_f32_16x16x32_bf16 v[130:133], v[150:153], v[200:203], v[130:133]
	v_mfma_f32_16x16x32_bf16 v[70:73], v[158:161], v[200:203], v[70:73]
	v_mfma_f32_16x16x32_bf16 v[78:81], v[150:153], v[208:211], v[78:81]
	v_mfma_f32_16x16x32_bf16 v[66:69], v[158:161], v[208:211], v[66:69]
	v_mfma_f32_16x16x32_bf16 v[138:141], v[150:153], v[228:231], v[138:141]
	v_mfma_f32_16x16x32_bf16 v[98:101], v[158:161], v[228:231], v[98:101]
	s_setprio 0
	s_barrier
	s_add_u32 s98, s52, 0x80
	s_addc_u32 s99, s53, 0
	s_add_u32 s100, s54, 0x80
	s_addc_u32 s101, s55, 0
	s_add_i32 s84, s75, s57
	s_mov_b32 m0, s84
	ds_read_b128 v[162:165], v221 offset:16384
	ds_read_b128 v[166:169], v221 offset:17408
	ds_read_b128 v[196:199], v221 offset:18432
	ds_read_b128 v[200:203], v221 offset:19456
	ds_read_b128 v[204:207], v221 offset:20480
	ds_read_b128 v[208:211], v221 offset:21504
	ds_read_b128 v[224:227], v221 offset:22528
	ds_read_b128 v[228:231], v221 offset:23552
	global_load_lds_dwordx4 v178, s[52:53]
	s_add_i32 m0, s84, 0x2000
	s_add_u32 s84, s52, 0x40000
	s_addc_u32 s85, s53, 0
	s_add_i32 s86, s76, s57
	global_load_lds_dwordx4 v182, s[52:53]
	s_mov_b32 m0, s86
	s_nop 0
	global_load_lds_dwordx4 v178, s[84:85]
	s_add_i32 m0, s86, 0x2000
	s_nop 0
	global_load_lds_dwordx4 v182, s[84:85]
	s_mov_b32 m0, s59
	s_nop 0
	global_load_lds_dwordx4 v176, s[54:55]
	s_mov_b32 m0, s62
	s_nop 0
	global_load_lds_dwordx4 v180, s[54:55]
	s_waitcnt vmcnt(8)
	s_waitcnt lgkmcnt(0)
	s_barrier
	s_setprio 1
	v_mfma_f32_16x16x32_bf16 v[94:97], v[30:33], v[162:165], 0
	v_mfma_f32_16x16x32_bf16 v[10:13], v[118:121], v[162:165], 0
	v_mfma_f32_16x16x32_bf16 v[90:93], v[30:33], v[196:199], 0
	v_mfma_f32_16x16x32_bf16 v[6:9], v[118:121], v[196:199], 0
	v_mfma_f32_16x16x32_bf16 v[86:89], v[30:33], v[204:207], 0
	v_mfma_f32_16x16x32_bf16 v[2:5], v[118:121], v[204:207], 0
	v_mfma_f32_16x16x32_bf16 v[26:29], v[118:121], v[224:227], 0
	v_mfma_f32_16x16x32_bf16 v[94:97], v[54:57], v[166:169], v[94:97]
	v_mfma_f32_16x16x32_bf16 v[10:13], v[122:125], v[166:169], v[10:13]
	v_mfma_f32_16x16x32_bf16 v[90:93], v[54:57], v[200:203], v[90:93]
	v_mfma_f32_16x16x32_bf16 v[6:9], v[122:125], v[200:203], v[6:9]
	v_mfma_f32_16x16x32_bf16 v[86:89], v[54:57], v[208:211], v[86:89]
	v_mfma_f32_16x16x32_bf16 v[2:5], v[122:125], v[208:211], v[2:5]
	v_mfma_f32_16x16x32_bf16 v[30:33], v[30:33], v[224:227], 0
	v_mfma_f32_16x16x32_bf16 v[26:29], v[122:125], v[228:231], v[26:29]
	v_mfma_f32_16x16x32_bf16 v[30:33], v[54:57], v[228:231], v[30:33]
	v_mfma_f32_16x16x32_bf16 v[22:25], v[154:157], v[162:165], 0
	v_mfma_f32_16x16x32_bf16 v[106:109], v[146:149], v[196:199], 0
	v_mfma_f32_16x16x32_bf16 v[18:21], v[154:157], v[196:199], 0
	v_mfma_f32_16x16x32_bf16 v[102:105], v[146:149], v[204:207], 0
	v_mfma_f32_16x16x32_bf16 v[14:17], v[154:157], v[204:207], 0
	v_mfma_f32_16x16x32_bf16 v[58:61], v[154:157], v[224:227], 0
	v_mfma_f32_16x16x32_bf16 v[54:57], v[146:149], v[162:165], 0
	v_mfma_f32_16x16x32_bf16 v[22:25], v[158:161], v[166:169], v[22:25]
	v_mfma_f32_16x16x32_bf16 v[106:109], v[150:153], v[200:203], v[106:109]
	v_mfma_f32_16x16x32_bf16 v[18:21], v[158:161], v[200:203], v[18:21]
	v_mfma_f32_16x16x32_bf16 v[102:105], v[150:153], v[208:211], v[102:105]
	v_mfma_f32_16x16x32_bf16 v[14:17], v[158:161], v[208:211], v[14:17]
	v_mfma_f32_16x16x32_bf16 v[110:113], v[146:149], v[224:227], 0
	v_mfma_f32_16x16x32_bf16 v[58:61], v[158:161], v[228:231], v[58:61]
	v_mfma_f32_16x16x32_bf16 v[54:57], v[150:153], v[166:169], v[54:57]
	v_mfma_f32_16x16x32_bf16 v[118:121], v[150:153], v[228:231], v[110:113]
	s_setprio 0
	s_barrier
	s_add_i32 s84, 0, 0x18000
	s_add_i32 s85, 0, 0x1c000
	v_add_u32_e32 v126, s84, v175
	v_add_u32_e32 v158, s85, v175
	ds_read_b128 v[110:113], v126
	ds_read_b128 v[114:117], v126 offset:1024
	ds_read_b128 v[122:125], v126 offset:2048
	ds_read_b128 v[126:129], v126 offset:3072
	ds_read_b128 v[146:149], v158
	ds_read_b128 v[150:153], v158 offset:1024
	ds_read_b128 v[154:157], v158 offset:2048
	ds_read_b128 v[158:161], v158 offset:3072
	s_add_u32 s54, s54, 0x40000
	s_addc_u32 s55, s55, 0
	s_mov_b32 m0, s63
	ds_read_b128 v[162:165], v221 offset:32768
	ds_read_b128 v[166:169], v221 offset:33792
	ds_read_b128 v[196:199], v221 offset:34816
	ds_read_b128 v[200:203], v221 offset:35840
	ds_read_b128 v[204:207], v221 offset:36864
	ds_read_b128 v[208:211], v221 offset:37888
	ds_read_b128 v[224:227], v221 offset:38912
	ds_read_b128 v[228:231], v221 offset:39936
	global_load_lds_dwordx4 v176, s[54:55]
	s_mov_b32 m0, s64
	s_nop 0
	global_load_lds_dwordx4 v180, s[54:55]
	s_waitcnt vmcnt(8)
	s_waitcnt lgkmcnt(0)
	s_barrier
	s_setprio 1
	v_mfma_f32_16x16x32_bf16 v[62:65], v[110:113], v[162:165], v[62:65]
	v_mfma_f32_16x16x32_bf16 v[42:45], v[122:125], v[162:165], v[42:45]
	v_mfma_f32_16x16x32_bf16 v[50:53], v[110:113], v[196:199], v[50:53]
	v_mfma_f32_16x16x32_bf16 v[38:41], v[122:125], v[196:199], v[38:41]
	v_mfma_f32_16x16x32_bf16 v[46:49], v[110:113], v[204:207], v[46:49]
	v_mfma_f32_16x16x32_bf16 v[34:37], v[122:125], v[204:207], v[34:37]
	v_mfma_f32_16x16x32_bf16 v[142:145], v[110:113], v[224:227], v[142:145]
	v_mfma_f32_16x16x32_bf16 v[82:85], v[122:125], v[224:227], v[82:85]
	v_mfma_f32_16x16x32_bf16 v[62:65], v[114:117], v[166:169], v[62:65]
	v_mfma_f32_16x16x32_bf16 v[42:45], v[126:129], v[166:169], v[42:45]
	v_mfma_f32_16x16x32_bf16 v[50:53], v[114:117], v[200:203], v[50:53]
	v_mfma_f32_16x16x32_bf16 v[38:41], v[126:129], v[200:203], v[38:41]
	v_mfma_f32_16x16x32_bf16 v[46:49], v[114:117], v[208:211], v[46:49]
	v_mfma_f32_16x16x32_bf16 v[34:37], v[126:129], v[208:211], v[34:37]
	v_mfma_f32_16x16x32_bf16 v[142:145], v[114:117], v[228:231], v[142:145]
	v_mfma_f32_16x16x32_bf16 v[82:85], v[126:129], v[228:231], v[82:85]
	v_mfma_f32_16x16x32_bf16 v[134:137], v[146:149], v[162:165], v[134:137]
	v_mfma_f32_16x16x32_bf16 v[74:77], v[154:157], v[162:165], v[74:77]
	v_mfma_f32_16x16x32_bf16 v[130:133], v[146:149], v[196:199], v[130:133]
	v_mfma_f32_16x16x32_bf16 v[70:73], v[154:157], v[196:199], v[70:73]
	v_mfma_f32_16x16x32_bf16 v[78:81], v[146:149], v[204:207], v[78:81]
	v_mfma_f32_16x16x32_bf16 v[66:69], v[154:157], v[204:207], v[66:69]
	v_mfma_f32_16x16x32_bf16 v[138:141], v[146:149], v[224:227], v[138:141]
	v_mfma_f32_16x16x32_bf16 v[98:101], v[154:157], v[224:227], v[98:101]
	v_mfma_f32_16x16x32_bf16 v[134:137], v[150:153], v[166:169], v[134:137]
	v_mfma_f32_16x16x32_bf16 v[74:77], v[158:161], v[166:169], v[74:77]
	v_mfma_f32_16x16x32_bf16 v[130:133], v[150:153], v[200:203], v[130:133]
	v_mfma_f32_16x16x32_bf16 v[70:73], v[158:161], v[200:203], v[70:73]
	v_mfma_f32_16x16x32_bf16 v[78:81], v[150:153], v[208:211], v[78:81]
	v_mfma_f32_16x16x32_bf16 v[66:69], v[158:161], v[208:211], v[66:69]
	v_mfma_f32_16x16x32_bf16 v[138:141], v[150:153], v[228:231], v[138:141]
	v_mfma_f32_16x16x32_bf16 v[98:101], v[158:161], v[228:231], v[98:101]
	s_setprio 0
	s_barrier
	s_add_i32 s54, s84, s57
	s_mov_b32 m0, s54
	ds_read_b128 v[162:165], v221 offset:49152
	ds_read_b128 v[166:169], v221 offset:50176
	ds_read_b128 v[196:199], v221 offset:51200
	ds_read_b128 v[200:203], v221 offset:52224
	ds_read_b128 v[204:207], v221 offset:53248
	ds_read_b128 v[208:211], v221 offset:54272
	ds_read_b128 v[224:227], v221 offset:55296
	ds_read_b128 v[228:231], v221 offset:56320
	global_load_lds_dwordx4 v178, s[98:99]
	s_add_i32 m0, s54, 0x2000
	s_add_u32 s52, s52, 0x40080
	s_addc_u32 s53, s53, 0
	s_add_i32 s54, s85, s57
	global_load_lds_dwordx4 v182, s[98:99]
	s_mov_b32 m0, s54
	s_nop 0
	global_load_lds_dwordx4 v178, s[52:53]
	s_add_i32 m0, s54, 0x2000
	s_nop 0
	global_load_lds_dwordx4 v182, s[52:53]
	s_mov_b32 m0, s70
	s_nop 0
	global_load_lds_dwordx4 v176, s[100:101]
	s_mov_b32 m0, s71
	s_nop 0
	global_load_lds_dwordx4 v180, s[100:101]
	s_waitcnt vmcnt(8)
	s_waitcnt lgkmcnt(0)
	s_barrier
	s_setprio 1
	v_mfma_f32_16x16x32_bf16 v[94:97], v[110:113], v[162:165], v[94:97]
	v_mfma_f32_16x16x32_bf16 v[10:13], v[122:125], v[162:165], v[10:13]
	v_mfma_f32_16x16x32_bf16 v[90:93], v[110:113], v[196:199], v[90:93]
	v_mfma_f32_16x16x32_bf16 v[6:9], v[122:125], v[196:199], v[6:9]
	v_mfma_f32_16x16x32_bf16 v[86:89], v[110:113], v[204:207], v[86:89]
	v_mfma_f32_16x16x32_bf16 v[2:5], v[122:125], v[204:207], v[2:5]
	v_mfma_f32_16x16x32_bf16 v[30:33], v[110:113], v[224:227], v[30:33]
	v_mfma_f32_16x16x32_bf16 v[26:29], v[122:125], v[224:227], v[26:29]
	v_mfma_f32_16x16x32_bf16 v[94:97], v[114:117], v[166:169], v[94:97]
	v_mfma_f32_16x16x32_bf16 v[10:13], v[126:129], v[166:169], v[10:13]
	v_mfma_f32_16x16x32_bf16 v[90:93], v[114:117], v[200:203], v[90:93]
	v_mfma_f32_16x16x32_bf16 v[6:9], v[126:129], v[200:203], v[6:9]
	v_mfma_f32_16x16x32_bf16 v[86:89], v[114:117], v[208:211], v[86:89]
	v_mfma_f32_16x16x32_bf16 v[2:5], v[126:129], v[208:211], v[2:5]
	v_mfma_f32_16x16x32_bf16 v[114:117], v[114:117], v[228:231], v[30:33]
	v_mfma_f32_16x16x32_bf16 v[26:29], v[126:129], v[228:231], v[26:29]
	v_mfma_f32_16x16x32_bf16 v[30:33], v[146:149], v[162:165], v[54:57]
	v_mfma_f32_16x16x32_bf16 v[110:113], v[150:153], v[166:169], v[30:33]
	v_mfma_f32_16x16x32_bf16 v[30:33], v[146:149], v[196:199], v[106:109]
	v_mfma_f32_16x16x32_bf16 v[106:109], v[150:153], v[200:203], v[30:33]
	v_mfma_f32_16x16x32_bf16 v[30:33], v[146:149], v[204:207], v[102:105]
	v_mfma_f32_16x16x32_bf16 v[102:105], v[150:153], v[208:211], v[30:33]
	v_mfma_f32_16x16x32_bf16 v[30:33], v[146:149], v[224:227], v[118:121]
	v_mfma_f32_16x16x32_bf16 v[22:25], v[154:157], v[162:165], v[22:25]
	v_mfma_f32_16x16x32_bf16 v[18:21], v[154:157], v[196:199], v[18:21]
	v_mfma_f32_16x16x32_bf16 v[14:17], v[154:157], v[204:207], v[14:17]
	v_mfma_f32_16x16x32_bf16 v[126:129], v[150:153], v[228:231], v[30:33]
	v_mfma_f32_16x16x32_bf16 v[30:33], v[154:157], v[224:227], v[58:61]
	v_mfma_f32_16x16x32_bf16 v[22:25], v[158:161], v[166:169], v[22:25]
	v_mfma_f32_16x16x32_bf16 v[18:21], v[158:161], v[200:203], v[18:21]
	v_mfma_f32_16x16x32_bf16 v[14:17], v[158:161], v[208:211], v[14:17]
	v_mfma_f32_16x16x32_bf16 v[58:61], v[158:161], v[228:231], v[30:33]
	s_setprio 0
	s_barrier
	s_add_i32 s93, s93, 2
	s_add_u32 s8, s8, 0x100
	s_addc_u32 s9, s9, 0
	s_add_u32 s91, s91, 0x100
	s_addc_u32 s92, s92, 0
	s_cmp_gt_u32 s93, 13
